# filter epilogue: expf's underflow/overflow selects removed (argument provably in [-15.4, 0] from indices alone; bit-identical)
# speedup vs baseline: 1.0197x; 1.0016x over previous
.LBB0_1332:
	s_waitcnt lgkmcnt(0)
	s_barrier
	ds_read_b32 v160, v158 offset:0
	ds_read_b32 v161, v158 offset:128
	ds_read_b32 v162, v159
	ds_read_b32 v163, v158 offset:1024
	ds_read_b32 v164, v158 offset:1152
	ds_read_b32 v165, v159 offset:8
	ds_read_b32 v166, v158 offset:2048
	ds_read_b32 v167, v158 offset:2176
	ds_read_b32 v168, v159 offset:16
	ds_read_b32 v169, v158 offset:3072
	ds_read_b32 v170, v158 offset:3200
	ds_read_b32 v171, v159 offset:24
	s_waitcnt vmcnt(0)
	s_waitcnt lgkmcnt(9)
	v_mfma_f32_32x32x2_f32 v[124:139], v160, v162, v[124:139]
	v_mfma_f32_32x32x2_f32 v[140:155], v161, v162, v[140:155]
	ds_read_b32 v160, v158 offset:4096
	ds_read_b32 v161, v158 offset:4224
	ds_read_b32 v162, v159 offset:32
	s_waitcnt lgkmcnt(9)
	v_mfma_f32_32x32x2_f32 v[124:139], v163, v165, v[124:139]
	v_mfma_f32_32x32x2_f32 v[140:155], v164, v165, v[140:155]
	ds_read_b32 v163, v158 offset:5120
	ds_read_b32 v164, v158 offset:5248
	ds_read_b32 v165, v159 offset:40
	s_waitcnt lgkmcnt(9)
	v_mfma_f32_32x32x2_f32 v[124:139], v166, v168, v[124:139]
	v_mfma_f32_32x32x2_f32 v[140:155], v167, v168, v[140:155]
	ds_read_b32 v166, v158 offset:6144
	ds_read_b32 v167, v158 offset:6272
	ds_read_b32 v168, v159 offset:48
	s_waitcnt lgkmcnt(9)
	v_mfma_f32_32x32x2_f32 v[124:139], v169, v171, v[124:139]
	v_mfma_f32_32x32x2_f32 v[140:155], v170, v171, v[140:155]
	ds_read_b32 v169, v158 offset:7168
	ds_read_b32 v170, v158 offset:7296
	ds_read_b32 v171, v159 offset:56
	s_waitcnt lgkmcnt(9)
	v_mfma_f32_32x32x2_f32 v[124:139], v160, v162, v[124:139]
	v_mfma_f32_32x32x2_f32 v[140:155], v161, v162, v[140:155]
	ds_read_b32 v160, v158 offset:8192
	ds_read_b32 v161, v158 offset:8320
	ds_read_b32 v162, v159 offset:64
	s_waitcnt lgkmcnt(9)
	v_mfma_f32_32x32x2_f32 v[124:139], v163, v165, v[124:139]
	v_mfma_f32_32x32x2_f32 v[140:155], v164, v165, v[140:155]
	ds_read_b32 v163, v158 offset:9216
	ds_read_b32 v164, v158 offset:9344
	ds_read_b32 v165, v159 offset:72
	s_waitcnt lgkmcnt(9)
	v_mfma_f32_32x32x2_f32 v[124:139], v166, v168, v[124:139]
	v_mfma_f32_32x32x2_f32 v[140:155], v167, v168, v[140:155]
	ds_read_b32 v166, v158 offset:10240
	ds_read_b32 v167, v158 offset:10368
	ds_read_b32 v168, v159 offset:80
	s_waitcnt lgkmcnt(9)
	v_mfma_f32_32x32x2_f32 v[124:139], v169, v171, v[124:139]
	v_mfma_f32_32x32x2_f32 v[140:155], v170, v171, v[140:155]
	ds_read_b32 v169, v158 offset:11264
	ds_read_b32 v170, v158 offset:11392
	ds_read_b32 v171, v159 offset:88
	s_waitcnt lgkmcnt(9)
	v_mfma_f32_32x32x2_f32 v[124:139], v160, v162, v[124:139]
	v_mfma_f32_32x32x2_f32 v[140:155], v161, v162, v[140:155]
	ds_read_b32 v160, v158 offset:12288
	ds_read_b32 v161, v158 offset:12416
	ds_read_b32 v162, v159 offset:96
	s_waitcnt lgkmcnt(9)
	v_mfma_f32_32x32x2_f32 v[124:139], v163, v165, v[124:139]
	v_mfma_f32_32x32x2_f32 v[140:155], v164, v165, v[140:155]
	ds_read_b32 v163, v158 offset:13312
	ds_read_b32 v164, v158 offset:13440
	ds_read_b32 v165, v159 offset:104
	s_waitcnt lgkmcnt(9)
	v_mfma_f32_32x32x2_f32 v[124:139], v166, v168, v[124:139]
	v_mfma_f32_32x32x2_f32 v[140:155], v167, v168, v[140:155]
	ds_read_b32 v166, v158 offset:14336
	ds_read_b32 v167, v158 offset:14464
	ds_read_b32 v168, v159 offset:112
	s_waitcnt lgkmcnt(9)
	v_mfma_f32_32x32x2_f32 v[124:139], v169, v171, v[124:139]
	v_mfma_f32_32x32x2_f32 v[140:155], v170, v171, v[140:155]
	ds_read_b32 v169, v158 offset:15360
	ds_read_b32 v170, v158 offset:15488
	ds_read_b32 v171, v159 offset:120
	s_waitcnt lgkmcnt(9)
	v_mfma_f32_32x32x2_f32 v[124:139], v160, v162, v[124:139]
	v_mfma_f32_32x32x2_f32 v[140:155], v161, v162, v[140:155]
	ds_read_b32 v160, v158 offset:16384
	ds_read_b32 v161, v158 offset:16512
	ds_read_b32 v162, v159 offset:128
	s_waitcnt lgkmcnt(9)
	v_mfma_f32_32x32x2_f32 v[124:139], v163, v165, v[124:139]
	v_mfma_f32_32x32x2_f32 v[140:155], v164, v165, v[140:155]
	ds_read_b32 v163, v158 offset:17408
	ds_read_b32 v164, v158 offset:17536
	ds_read_b32 v165, v159 offset:136
	s_waitcnt lgkmcnt(9)
	v_mfma_f32_32x32x2_f32 v[124:139], v166, v168, v[124:139]
	v_mfma_f32_32x32x2_f32 v[140:155], v167, v168, v[140:155]
	ds_read_b32 v166, v158 offset:18432
	ds_read_b32 v167, v158 offset:18560
	ds_read_b32 v168, v159 offset:144
	s_waitcnt lgkmcnt(9)
	v_mfma_f32_32x32x2_f32 v[124:139], v169, v171, v[124:139]
	v_mfma_f32_32x32x2_f32 v[140:155], v170, v171, v[140:155]
	ds_read_b32 v169, v158 offset:19456
	ds_read_b32 v170, v158 offset:19584
	ds_read_b32 v171, v159 offset:152
	s_waitcnt lgkmcnt(9)
	v_mfma_f32_32x32x2_f32 v[124:139], v160, v162, v[124:139]
	v_mfma_f32_32x32x2_f32 v[140:155], v161, v162, v[140:155]
	ds_read_b32 v160, v158 offset:20480
	ds_read_b32 v161, v158 offset:20608
	ds_read_b32 v162, v159 offset:160
	s_waitcnt lgkmcnt(9)
	v_mfma_f32_32x32x2_f32 v[124:139], v163, v165, v[124:139]
	v_mfma_f32_32x32x2_f32 v[140:155], v164, v165, v[140:155]
	ds_read_b32 v163, v158 offset:21504
	ds_read_b32 v164, v158 offset:21632
	ds_read_b32 v165, v159 offset:168
	s_waitcnt lgkmcnt(9)
	v_mfma_f32_32x32x2_f32 v[124:139], v166, v168, v[124:139]
	v_mfma_f32_32x32x2_f32 v[140:155], v167, v168, v[140:155]
	ds_read_b32 v166, v158 offset:22528
	ds_read_b32 v167, v158 offset:22656
	ds_read_b32 v168, v159 offset:176
	s_waitcnt lgkmcnt(9)
	v_mfma_f32_32x32x2_f32 v[124:139], v169, v171, v[124:139]
	v_mfma_f32_32x32x2_f32 v[140:155], v170, v171, v[140:155]
	ds_read_b32 v169, v158 offset:23552
	ds_read_b32 v170, v158 offset:23680
	ds_read_b32 v171, v159 offset:184
	s_waitcnt lgkmcnt(9)
	v_mfma_f32_32x32x2_f32 v[124:139], v160, v162, v[124:139]
	v_mfma_f32_32x32x2_f32 v[140:155], v161, v162, v[140:155]
	ds_read_b32 v160, v158 offset:24576
	ds_read_b32 v161, v158 offset:24704
	ds_read_b32 v162, v159 offset:192
	s_waitcnt lgkmcnt(9)
	v_mfma_f32_32x32x2_f32 v[124:139], v163, v165, v[124:139]
	v_mfma_f32_32x32x2_f32 v[140:155], v164, v165, v[140:155]
	ds_read_b32 v163, v158 offset:25600
	ds_read_b32 v164, v158 offset:25728
	ds_read_b32 v165, v159 offset:200
	s_waitcnt lgkmcnt(9)
	v_mfma_f32_32x32x2_f32 v[124:139], v166, v168, v[124:139]
	v_mfma_f32_32x32x2_f32 v[140:155], v167, v168, v[140:155]
	ds_read_b32 v166, v158 offset:26624
	ds_read_b32 v167, v158 offset:26752
	ds_read_b32 v168, v159 offset:208
	s_waitcnt lgkmcnt(9)
	v_mfma_f32_32x32x2_f32 v[124:139], v169, v171, v[124:139]
	v_mfma_f32_32x32x2_f32 v[140:155], v170, v171, v[140:155]
	ds_read_b32 v169, v158 offset:27648
	ds_read_b32 v170, v158 offset:27776
	ds_read_b32 v171, v159 offset:216
	s_waitcnt lgkmcnt(9)
	v_mfma_f32_32x32x2_f32 v[124:139], v160, v162, v[124:139]
	v_mfma_f32_32x32x2_f32 v[140:155], v161, v162, v[140:155]
	ds_read_b32 v160, v158 offset:28672
	ds_read_b32 v161, v158 offset:28800
	ds_read_b32 v162, v159 offset:224
	s_waitcnt lgkmcnt(9)
	v_mfma_f32_32x32x2_f32 v[124:139], v163, v165, v[124:139]
	v_mfma_f32_32x32x2_f32 v[140:155], v164, v165, v[140:155]
	ds_read_b32 v163, v158 offset:29696
	ds_read_b32 v164, v158 offset:29824
	ds_read_b32 v165, v159 offset:232
	s_waitcnt lgkmcnt(9)
	v_mfma_f32_32x32x2_f32 v[124:139], v166, v168, v[124:139]
	v_mfma_f32_32x32x2_f32 v[140:155], v167, v168, v[140:155]
	ds_read_b32 v166, v158 offset:30720
	ds_read_b32 v167, v158 offset:30848
	ds_read_b32 v168, v159 offset:240
	s_waitcnt lgkmcnt(9)
	v_mfma_f32_32x32x2_f32 v[124:139], v169, v171, v[124:139]
	v_mfma_f32_32x32x2_f32 v[140:155], v170, v171, v[140:155]
	ds_read_b32 v169, v158 offset:31744
	ds_read_b32 v170, v158 offset:31872
	ds_read_b32 v171, v159 offset:248
	s_waitcnt lgkmcnt(9)
	v_mfma_f32_32x32x2_f32 v[124:139], v160, v162, v[124:139]
	v_mfma_f32_32x32x2_f32 v[140:155], v161, v162, v[140:155]
	s_waitcnt lgkmcnt(6)
	v_mfma_f32_32x32x2_f32 v[124:139], v163, v165, v[124:139]
	v_mfma_f32_32x32x2_f32 v[140:155], v164, v165, v[140:155]
	s_waitcnt lgkmcnt(3)
	v_mfma_f32_32x32x2_f32 v[124:139], v166, v168, v[124:139]
	v_mfma_f32_32x32x2_f32 v[140:155], v167, v168, v[140:155]
	s_waitcnt lgkmcnt(0)
	v_mfma_f32_32x32x2_f32 v[124:139], v169, v171, v[124:139]
	v_mfma_f32_32x32x2_f32 v[140:155], v170, v171, v[140:155]
	v_lshl_add_u32 v172, s10, 7, v156
	v_lshl_add_u32 v172, v109, 5, v172
	s_add_i32 s2, s9, -1
	v_cvt_f32_u32_e32 v54, s2
	v_cvt_f32_i32_e32 v11, v172
	v_mov_b32_e32 v60, 0xc0447cbd
	v_lshl_add_u32 v174, v108, 6, s11
	v_lshl_add_u32 v174, v157, 2, v174
	v_mad_i64_i32 v[176:177], s[2:3], s9, v174, 0
	v_lshl_add_u64 v[176:177], v[176:177], 2, s[0:1]
	v_mov_b32_e32 v180, v172
	v_mov_b32_e32 v181, v1
	v_lshl_add_u64 v[176:177], v[180:181], 2, v[176:177]
	v_div_scale_f32 v24, s[2:3], v54, v54, -v11
	v_rcp_f32_e32 v25, v24
	s_mov_b32 s4, 0x3fb8aa3b
	s_mov_b32 s5, 0xc2ce8ed0
	s_mov_b32 s6, 0x42b17218
	v_fma_f32 v39, -v24, v25, 1.0
	v_fmac_f32_e32 v25, v39, v25
	v_div_scale_f32 v39, vcc, -v11, v54, -v11
	v_mul_f32_e32 v56, v39, v25
	v_fma_f32 v57, -v24, v56, v39
	v_fmac_f32_e32 v56, v57, v25
	v_fma_f32 v24, -v24, v56, v39
	v_div_fmas_f32 v24, v24, v25, v56
	v_div_fixup_f32 v173, v24, v54, -v11
	s_lshl_b32 s14, s9, 2
	s_mov_b32 s15, 0
	s_mul_i32 s16, s14, 5
	s_mov_b32 s17, 0
	s_nop 7
	s_nop 7
	s_nop 3
	v_and_b32_e32 v24, 0x1ff, v174
	v_cvt_f32_u32_e32 v24, v24
	v_fmamk_f32 v55, v24, 0xbcc4df2d, v60
	v_mul_f32_e64 v24, |v55|, v173
	v_mul_f32_e32 v25, 0x3fb8aa3b, v24
	v_fma_f32 v39, v24, s4, -v25
	v_rndne_f32_e32 v56, v25
	v_fmac_f32_e32 v39, 0x32a5705f, v24
	v_sub_f32_e32 v25, v25, v56
	v_add_f32_e32 v25, v25, v39
	v_exp_f32_e32 v25, v25
	v_cvt_i32_f32_e32 v39, v56
	v_ldexp_f32 v25, v25, v39
	v_mul_f32_e32 v124, v25, v124
	global_store_dword v[176:177], v124, off
	v_add_u32_e32 v174, 1, v174
	v_lshl_add_u64 v[176:177], v[176:177], 0, s[14:15]
	v_and_b32_e32 v24, 0x1ff, v174
	v_cvt_f32_u32_e32 v24, v24
	v_fmamk_f32 v55, v24, 0xbcc4df2d, v60
	v_mul_f32_e64 v24, |v55|, v173
	v_mul_f32_e32 v25, 0x3fb8aa3b, v24
	v_fma_f32 v39, v24, s4, -v25
	v_rndne_f32_e32 v56, v25
	v_fmac_f32_e32 v39, 0x32a5705f, v24
	v_sub_f32_e32 v25, v25, v56
	v_add_f32_e32 v25, v25, v39
	v_exp_f32_e32 v25, v25
	v_cvt_i32_f32_e32 v39, v56
	v_ldexp_f32 v25, v25, v39
	v_mul_f32_e32 v125, v25, v125
	global_store_dword v[176:177], v125, off
	v_add_u32_e32 v174, 1, v174
	v_lshl_add_u64 v[176:177], v[176:177], 0, s[14:15]
	v_and_b32_e32 v24, 0x1ff, v174
	v_cvt_f32_u32_e32 v24, v24
	v_fmamk_f32 v55, v24, 0xbcc4df2d, v60
	v_mul_f32_e64 v24, |v55|, v173
	v_mul_f32_e32 v25, 0x3fb8aa3b, v24
	v_fma_f32 v39, v24, s4, -v25
	v_rndne_f32_e32 v56, v25
	v_fmac_f32_e32 v39, 0x32a5705f, v24
	v_sub_f32_e32 v25, v25, v56
	v_add_f32_e32 v25, v25, v39
	v_exp_f32_e32 v25, v25
	v_cvt_i32_f32_e32 v39, v56
	v_ldexp_f32 v25, v25, v39
	v_mul_f32_e32 v126, v25, v126
	global_store_dword v[176:177], v126, off
	v_add_u32_e32 v174, 1, v174
	v_lshl_add_u64 v[176:177], v[176:177], 0, s[14:15]
	v_and_b32_e32 v24, 0x1ff, v174
	v_cvt_f32_u32_e32 v24, v24
	v_fmamk_f32 v55, v24, 0xbcc4df2d, v60
	v_mul_f32_e64 v24, |v55|, v173
	v_mul_f32_e32 v25, 0x3fb8aa3b, v24
	v_fma_f32 v39, v24, s4, -v25
	v_rndne_f32_e32 v56, v25
	v_fmac_f32_e32 v39, 0x32a5705f, v24
	v_sub_f32_e32 v25, v25, v56
	v_add_f32_e32 v25, v25, v39
	v_exp_f32_e32 v25, v25
	v_cvt_i32_f32_e32 v39, v56
	v_ldexp_f32 v25, v25, v39
	v_mul_f32_e32 v127, v25, v127
	global_store_dword v[176:177], v127, off
	v_add_u32_e32 v174, 5, v174
	v_lshl_add_u64 v[176:177], v[176:177], 0, s[16:17]
	v_and_b32_e32 v24, 0x1ff, v174
	v_cvt_f32_u32_e32 v24, v24
	v_fmamk_f32 v55, v24, 0xbcc4df2d, v60
	v_mul_f32_e64 v24, |v55|, v173
	v_mul_f32_e32 v25, 0x3fb8aa3b, v24
	v_fma_f32 v39, v24, s4, -v25
	v_rndne_f32_e32 v56, v25
	v_fmac_f32_e32 v39, 0x32a5705f, v24
	v_sub_f32_e32 v25, v25, v56
	v_add_f32_e32 v25, v25, v39
	v_exp_f32_e32 v25, v25
	v_cvt_i32_f32_e32 v39, v56
	v_ldexp_f32 v25, v25, v39
	v_mul_f32_e32 v128, v25, v128
	global_store_dword v[176:177], v128, off
	v_add_u32_e32 v174, 1, v174
	v_lshl_add_u64 v[176:177], v[176:177], 0, s[14:15]
	v_and_b32_e32 v24, 0x1ff, v174
	v_cvt_f32_u32_e32 v24, v24
	v_fmamk_f32 v55, v24, 0xbcc4df2d, v60
	v_mul_f32_e64 v24, |v55|, v173
	v_mul_f32_e32 v25, 0x3fb8aa3b, v24
	v_fma_f32 v39, v24, s4, -v25
	v_rndne_f32_e32 v56, v25
	v_fmac_f32_e32 v39, 0x32a5705f, v24
	v_sub_f32_e32 v25, v25, v56
	v_add_f32_e32 v25, v25, v39
	v_exp_f32_e32 v25, v25
	v_cvt_i32_f32_e32 v39, v56
	v_ldexp_f32 v25, v25, v39
	v_mul_f32_e32 v129, v25, v129
	global_store_dword v[176:177], v129, off
	v_add_u32_e32 v174, 1, v174
	v_lshl_add_u64 v[176:177], v[176:177], 0, s[14:15]
	v_and_b32_e32 v24, 0x1ff, v174
	v_cvt_f32_u32_e32 v24, v24
	v_fmamk_f32 v55, v24, 0xbcc4df2d, v60
	v_mul_f32_e64 v24, |v55|, v173
	v_mul_f32_e32 v25, 0x3fb8aa3b, v24
	v_fma_f32 v39, v24, s4, -v25
	v_rndne_f32_e32 v56, v25
	v_fmac_f32_e32 v39, 0x32a5705f, v24
	v_sub_f32_e32 v25, v25, v56
	v_add_f32_e32 v25, v25, v39
	v_exp_f32_e32 v25, v25
	v_cvt_i32_f32_e32 v39, v56
	v_ldexp_f32 v25, v25, v39
	v_mul_f32_e32 v130, v25, v130
	global_store_dword v[176:177], v130, off
	v_add_u32_e32 v174, 1, v174
	v_lshl_add_u64 v[176:177], v[176:177], 0, s[14:15]
	v_and_b32_e32 v24, 0x1ff, v174
	v_cvt_f32_u32_e32 v24, v24
	v_fmamk_f32 v55, v24, 0xbcc4df2d, v60
	v_mul_f32_e64 v24, |v55|, v173
	v_mul_f32_e32 v25, 0x3fb8aa3b, v24
	v_fma_f32 v39, v24, s4, -v25
	v_rndne_f32_e32 v56, v25
	v_fmac_f32_e32 v39, 0x32a5705f, v24
	v_sub_f32_e32 v25, v25, v56
	v_add_f32_e32 v25, v25, v39
	v_exp_f32_e32 v25, v25
	v_cvt_i32_f32_e32 v39, v56
	v_ldexp_f32 v25, v25, v39
	v_mul_f32_e32 v131, v25, v131
	global_store_dword v[176:177], v131, off
	v_add_u32_e32 v174, 5, v174
	v_lshl_add_u64 v[176:177], v[176:177], 0, s[16:17]
	v_and_b32_e32 v24, 0x1ff, v174
	v_cvt_f32_u32_e32 v24, v24
	v_fmamk_f32 v55, v24, 0xbcc4df2d, v60
	v_mul_f32_e64 v24, |v55|, v173
	v_mul_f32_e32 v25, 0x3fb8aa3b, v24
	v_fma_f32 v39, v24, s4, -v25
	v_rndne_f32_e32 v56, v25
	v_fmac_f32_e32 v39, 0x32a5705f, v24
	v_sub_f32_e32 v25, v25, v56
	v_add_f32_e32 v25, v25, v39
	v_exp_f32_e32 v25, v25
	v_cvt_i32_f32_e32 v39, v56
	v_ldexp_f32 v25, v25, v39
	v_mul_f32_e32 v132, v25, v132
	global_store_dword v[176:177], v132, off
	v_add_u32_e32 v174, 1, v174
	v_lshl_add_u64 v[176:177], v[176:177], 0, s[14:15]
	v_and_b32_e32 v24, 0x1ff, v174
	v_cvt_f32_u32_e32 v24, v24
	v_fmamk_f32 v55, v24, 0xbcc4df2d, v60
	v_mul_f32_e64 v24, |v55|, v173
	v_mul_f32_e32 v25, 0x3fb8aa3b, v24
	v_fma_f32 v39, v24, s4, -v25
	v_rndne_f32_e32 v56, v25
	v_fmac_f32_e32 v39, 0x32a5705f, v24
	v_sub_f32_e32 v25, v25, v56
	v_add_f32_e32 v25, v25, v39
	v_exp_f32_e32 v25, v25
	v_cvt_i32_f32_e32 v39, v56
	v_ldexp_f32 v25, v25, v39
	v_mul_f32_e32 v133, v25, v133
	global_store_dword v[176:177], v133, off
	v_add_u32_e32 v174, 1, v174
	v_lshl_add_u64 v[176:177], v[176:177], 0, s[14:15]
	v_and_b32_e32 v24, 0x1ff, v174
	v_cvt_f32_u32_e32 v24, v24
	v_fmamk_f32 v55, v24, 0xbcc4df2d, v60
	v_mul_f32_e64 v24, |v55|, v173
	v_mul_f32_e32 v25, 0x3fb8aa3b, v24
	v_fma_f32 v39, v24, s4, -v25
	v_rndne_f32_e32 v56, v25
	v_fmac_f32_e32 v39, 0x32a5705f, v24
	v_sub_f32_e32 v25, v25, v56
	v_add_f32_e32 v25, v25, v39
	v_exp_f32_e32 v25, v25
	v_cvt_i32_f32_e32 v39, v56
	v_ldexp_f32 v25, v25, v39
	v_mul_f32_e32 v134, v25, v134
	global_store_dword v[176:177], v134, off
	v_add_u32_e32 v174, 1, v174
	v_lshl_add_u64 v[176:177], v[176:177], 0, s[14:15]
	v_and_b32_e32 v24, 0x1ff, v174
	v_cvt_f32_u32_e32 v24, v24
	v_fmamk_f32 v55, v24, 0xbcc4df2d, v60
	v_mul_f32_e64 v24, |v55|, v173
	v_mul_f32_e32 v25, 0x3fb8aa3b, v24
	v_fma_f32 v39, v24, s4, -v25
	v_rndne_f32_e32 v56, v25
	v_fmac_f32_e32 v39, 0x32a5705f, v24
	v_sub_f32_e32 v25, v25, v56
	v_add_f32_e32 v25, v25, v39
	v_exp_f32_e32 v25, v25
	v_cvt_i32_f32_e32 v39, v56
	v_ldexp_f32 v25, v25, v39
	v_mul_f32_e32 v135, v25, v135
	global_store_dword v[176:177], v135, off
	v_add_u32_e32 v174, 5, v174
	v_lshl_add_u64 v[176:177], v[176:177], 0, s[16:17]
	v_and_b32_e32 v24, 0x1ff, v174
	v_cvt_f32_u32_e32 v24, v24
	v_fmamk_f32 v55, v24, 0xbcc4df2d, v60
	v_mul_f32_e64 v24, |v55|, v173
	v_mul_f32_e32 v25, 0x3fb8aa3b, v24
	v_fma_f32 v39, v24, s4, -v25
	v_rndne_f32_e32 v56, v25
	v_fmac_f32_e32 v39, 0x32a5705f, v24
	v_sub_f32_e32 v25, v25, v56
	v_add_f32_e32 v25, v25, v39
	v_exp_f32_e32 v25, v25
	v_cvt_i32_f32_e32 v39, v56
	v_ldexp_f32 v25, v25, v39
	v_mul_f32_e32 v136, v25, v136
	global_store_dword v[176:177], v136, off
	v_add_u32_e32 v174, 1, v174
	v_lshl_add_u64 v[176:177], v[176:177], 0, s[14:15]
	v_and_b32_e32 v24, 0x1ff, v174
	v_cvt_f32_u32_e32 v24, v24
	v_fmamk_f32 v55, v24, 0xbcc4df2d, v60
	v_mul_f32_e64 v24, |v55|, v173
	v_mul_f32_e32 v25, 0x3fb8aa3b, v24
	v_fma_f32 v39, v24, s4, -v25
	v_rndne_f32_e32 v56, v25
	v_fmac_f32_e32 v39, 0x32a5705f, v24
	v_sub_f32_e32 v25, v25, v56
	v_add_f32_e32 v25, v25, v39
	v_exp_f32_e32 v25, v25
	v_cvt_i32_f32_e32 v39, v56
	v_ldexp_f32 v25, v25, v39
	v_mul_f32_e32 v137, v25, v137
	global_store_dword v[176:177], v137, off
	v_add_u32_e32 v174, 1, v174
	v_lshl_add_u64 v[176:177], v[176:177], 0, s[14:15]
	v_and_b32_e32 v24, 0x1ff, v174
	v_cvt_f32_u32_e32 v24, v24
	v_fmamk_f32 v55, v24, 0xbcc4df2d, v60
	v_mul_f32_e64 v24, |v55|, v173
	v_mul_f32_e32 v25, 0x3fb8aa3b, v24
	v_fma_f32 v39, v24, s4, -v25
	v_rndne_f32_e32 v56, v25
	v_fmac_f32_e32 v39, 0x32a5705f, v24
	v_sub_f32_e32 v25, v25, v56
	v_add_f32_e32 v25, v25, v39
	v_exp_f32_e32 v25, v25
	v_cvt_i32_f32_e32 v39, v56
	v_ldexp_f32 v25, v25, v39
	v_mul_f32_e32 v138, v25, v138
	global_store_dword v[176:177], v138, off
	v_add_u32_e32 v174, 1, v174
	v_lshl_add_u64 v[176:177], v[176:177], 0, s[14:15]
	v_and_b32_e32 v24, 0x1ff, v174
	v_cvt_f32_u32_e32 v24, v24
	v_fmamk_f32 v55, v24, 0xbcc4df2d, v60
	v_mul_f32_e64 v24, |v55|, v173
	v_mul_f32_e32 v25, 0x3fb8aa3b, v24
	v_fma_f32 v39, v24, s4, -v25
	v_rndne_f32_e32 v56, v25
	v_fmac_f32_e32 v39, 0x32a5705f, v24
	v_sub_f32_e32 v25, v25, v56
	v_add_f32_e32 v25, v25, v39
	v_exp_f32_e32 v25, v25
	v_cvt_i32_f32_e32 v39, v56
	v_ldexp_f32 v25, v25, v39
	v_mul_f32_e32 v139, v25, v139
	global_store_dword v[176:177], v139, off
	v_add_u32_e32 v174, 5, v174
	v_lshl_add_u64 v[176:177], v[176:177], 0, s[16:17]
	v_and_b32_e32 v24, 0x1ff, v174
	v_cvt_f32_u32_e32 v24, v24
	v_fmamk_f32 v55, v24, 0xbcc4df2d, v60
	v_mul_f32_e64 v24, |v55|, v173
	v_mul_f32_e32 v25, 0x3fb8aa3b, v24
	v_fma_f32 v39, v24, s4, -v25
	v_rndne_f32_e32 v56, v25
	v_fmac_f32_e32 v39, 0x32a5705f, v24
	v_sub_f32_e32 v25, v25, v56
	v_add_f32_e32 v25, v25, v39
	v_exp_f32_e32 v25, v25
	v_cvt_i32_f32_e32 v39, v56
	v_ldexp_f32 v25, v25, v39
	v_mul_f32_e32 v140, v25, v140
	global_store_dword v[176:177], v140, off
	v_add_u32_e32 v174, 1, v174
	v_lshl_add_u64 v[176:177], v[176:177], 0, s[14:15]
	v_and_b32_e32 v24, 0x1ff, v174
	v_cvt_f32_u32_e32 v24, v24
	v_fmamk_f32 v55, v24, 0xbcc4df2d, v60
	v_mul_f32_e64 v24, |v55|, v173
	v_mul_f32_e32 v25, 0x3fb8aa3b, v24
	v_fma_f32 v39, v24, s4, -v25
	v_rndne_f32_e32 v56, v25
	v_fmac_f32_e32 v39, 0x32a5705f, v24
	v_sub_f32_e32 v25, v25, v56
	v_add_f32_e32 v25, v25, v39
	v_exp_f32_e32 v25, v25
	v_cvt_i32_f32_e32 v39, v56
	v_ldexp_f32 v25, v25, v39
	v_mul_f32_e32 v141, v25, v141
	global_store_dword v[176:177], v141, off
	v_add_u32_e32 v174, 1, v174
	v_lshl_add_u64 v[176:177], v[176:177], 0, s[14:15]
	v_and_b32_e32 v24, 0x1ff, v174
	v_cvt_f32_u32_e32 v24, v24
	v_fmamk_f32 v55, v24, 0xbcc4df2d, v60
	v_mul_f32_e64 v24, |v55|, v173
	v_mul_f32_e32 v25, 0x3fb8aa3b, v24
	v_fma_f32 v39, v24, s4, -v25
	v_rndne_f32_e32 v56, v25
	v_fmac_f32_e32 v39, 0x32a5705f, v24
	v_sub_f32_e32 v25, v25, v56
	v_add_f32_e32 v25, v25, v39
	v_exp_f32_e32 v25, v25
	v_cvt_i32_f32_e32 v39, v56
	v_ldexp_f32 v25, v25, v39
	v_mul_f32_e32 v142, v25, v142
	global_store_dword v[176:177], v142, off
	v_add_u32_e32 v174, 1, v174
	v_lshl_add_u64 v[176:177], v[176:177], 0, s[14:15]
	v_and_b32_e32 v24, 0x1ff, v174
	v_cvt_f32_u32_e32 v24, v24
	v_fmamk_f32 v55, v24, 0xbcc4df2d, v60
	v_mul_f32_e64 v24, |v55|, v173
	v_mul_f32_e32 v25, 0x3fb8aa3b, v24
	v_fma_f32 v39, v24, s4, -v25
	v_rndne_f32_e32 v56, v25
	v_fmac_f32_e32 v39, 0x32a5705f, v24
	v_sub_f32_e32 v25, v25, v56
	v_add_f32_e32 v25, v25, v39
	v_exp_f32_e32 v25, v25
	v_cvt_i32_f32_e32 v39, v56
	v_ldexp_f32 v25, v25, v39
	v_mul_f32_e32 v143, v25, v143
	global_store_dword v[176:177], v143, off
	v_add_u32_e32 v174, 5, v174
	v_lshl_add_u64 v[176:177], v[176:177], 0, s[16:17]
	v_and_b32_e32 v24, 0x1ff, v174
	v_cvt_f32_u32_e32 v24, v24
	v_fmamk_f32 v55, v24, 0xbcc4df2d, v60
	v_mul_f32_e64 v24, |v55|, v173
	v_mul_f32_e32 v25, 0x3fb8aa3b, v24
	v_fma_f32 v39, v24, s4, -v25
	v_rndne_f32_e32 v56, v25
	v_fmac_f32_e32 v39, 0x32a5705f, v24
	v_sub_f32_e32 v25, v25, v56
	v_add_f32_e32 v25, v25, v39
	v_exp_f32_e32 v25, v25
	v_cvt_i32_f32_e32 v39, v56
	v_ldexp_f32 v25, v25, v39
	v_mul_f32_e32 v144, v25, v144
	global_store_dword v[176:177], v144, off
	v_add_u32_e32 v174, 1, v174
	v_lshl_add_u64 v[176:177], v[176:177], 0, s[14:15]
	v_and_b32_e32 v24, 0x1ff, v174
	v_cvt_f32_u32_e32 v24, v24
	v_fmamk_f32 v55, v24, 0xbcc4df2d, v60
	v_mul_f32_e64 v24, |v55|, v173
	v_mul_f32_e32 v25, 0x3fb8aa3b, v24
	v_fma_f32 v39, v24, s4, -v25
	v_rndne_f32_e32 v56, v25
	v_fmac_f32_e32 v39, 0x32a5705f, v24
	v_sub_f32_e32 v25, v25, v56
	v_add_f32_e32 v25, v25, v39
	v_exp_f32_e32 v25, v25
	v_cvt_i32_f32_e32 v39, v56
	v_ldexp_f32 v25, v25, v39
	v_mul_f32_e32 v145, v25, v145
	global_store_dword v[176:177], v145, off
	v_add_u32_e32 v174, 1, v174
	v_lshl_add_u64 v[176:177], v[176:177], 0, s[14:15]
	v_and_b32_e32 v24, 0x1ff, v174
	v_cvt_f32_u32_e32 v24, v24
	v_fmamk_f32 v55, v24, 0xbcc4df2d, v60
	v_mul_f32_e64 v24, |v55|, v173
	v_mul_f32_e32 v25, 0x3fb8aa3b, v24
	v_fma_f32 v39, v24, s4, -v25
	v_rndne_f32_e32 v56, v25
	v_fmac_f32_e32 v39, 0x32a5705f, v24
	v_sub_f32_e32 v25, v25, v56
	v_add_f32_e32 v25, v25, v39
	v_exp_f32_e32 v25, v25
	v_cvt_i32_f32_e32 v39, v56
	v_ldexp_f32 v25, v25, v39
	v_mul_f32_e32 v146, v25, v146
	global_store_dword v[176:177], v146, off
	v_add_u32_e32 v174, 1, v174
	v_lshl_add_u64 v[176:177], v[176:177], 0, s[14:15]
	v_and_b32_e32 v24, 0x1ff, v174
	v_cvt_f32_u32_e32 v24, v24
	v_fmamk_f32 v55, v24, 0xbcc4df2d, v60
	v_mul_f32_e64 v24, |v55|, v173
	v_mul_f32_e32 v25, 0x3fb8aa3b, v24
	v_fma_f32 v39, v24, s4, -v25
	v_rndne_f32_e32 v56, v25
	v_fmac_f32_e32 v39, 0x32a5705f, v24
	v_sub_f32_e32 v25, v25, v56
	v_add_f32_e32 v25, v25, v39
	v_exp_f32_e32 v25, v25
	v_cvt_i32_f32_e32 v39, v56
	v_ldexp_f32 v25, v25, v39
	v_mul_f32_e32 v147, v25, v147
	global_store_dword v[176:177], v147, off
	v_add_u32_e32 v174, 5, v174
	v_lshl_add_u64 v[176:177], v[176:177], 0, s[16:17]
	v_and_b32_e32 v24, 0x1ff, v174
	v_cvt_f32_u32_e32 v24, v24
	v_fmamk_f32 v55, v24, 0xbcc4df2d, v60
	v_mul_f32_e64 v24, |v55|, v173
	v_mul_f32_e32 v25, 0x3fb8aa3b, v24
	v_fma_f32 v39, v24, s4, -v25
	v_rndne_f32_e32 v56, v25
	v_fmac_f32_e32 v39, 0x32a5705f, v24
	v_sub_f32_e32 v25, v25, v56
	v_add_f32_e32 v25, v25, v39
	v_exp_f32_e32 v25, v25
	v_cvt_i32_f32_e32 v39, v56
	v_ldexp_f32 v25, v25, v39
	v_mul_f32_e32 v148, v25, v148
	global_store_dword v[176:177], v148, off
	v_add_u32_e32 v174, 1, v174
	v_lshl_add_u64 v[176:177], v[176:177], 0, s[14:15]
	v_and_b32_e32 v24, 0x1ff, v174
	v_cvt_f32_u32_e32 v24, v24
	v_fmamk_f32 v55, v24, 0xbcc4df2d, v60
	v_mul_f32_e64 v24, |v55|, v173
	v_mul_f32_e32 v25, 0x3fb8aa3b, v24
	v_fma_f32 v39, v24, s4, -v25
	v_rndne_f32_e32 v56, v25
	v_fmac_f32_e32 v39, 0x32a5705f, v24
	v_sub_f32_e32 v25, v25, v56
	v_add_f32_e32 v25, v25, v39
	v_exp_f32_e32 v25, v25
	v_cvt_i32_f32_e32 v39, v56
	v_ldexp_f32 v25, v25, v39
	v_mul_f32_e32 v149, v25, v149
	global_store_dword v[176:177], v149, off
	v_add_u32_e32 v174, 1, v174
	v_lshl_add_u64 v[176:177], v[176:177], 0, s[14:15]
	v_and_b32_e32 v24, 0x1ff, v174
	v_cvt_f32_u32_e32 v24, v24
	v_fmamk_f32 v55, v24, 0xbcc4df2d, v60
	v_mul_f32_e64 v24, |v55|, v173
	v_mul_f32_e32 v25, 0x3fb8aa3b, v24
	v_fma_f32 v39, v24, s4, -v25
	v_rndne_f32_e32 v56, v25
	v_fmac_f32_e32 v39, 0x32a5705f, v24
	v_sub_f32_e32 v25, v25, v56
	v_add_f32_e32 v25, v25, v39
	v_exp_f32_e32 v25, v25
	v_cvt_i32_f32_e32 v39, v56
	v_ldexp_f32 v25, v25, v39
	v_mul_f32_e32 v150, v25, v150
	global_store_dword v[176:177], v150, off
	v_add_u32_e32 v174, 1, v174
	v_lshl_add_u64 v[176:177], v[176:177], 0, s[14:15]
	v_and_b32_e32 v24, 0x1ff, v174
	v_cvt_f32_u32_e32 v24, v24
	v_fmamk_f32 v55, v24, 0xbcc4df2d, v60
	v_mul_f32_e64 v24, |v55|, v173
	v_mul_f32_e32 v25, 0x3fb8aa3b, v24
	v_fma_f32 v39, v24, s4, -v25
	v_rndne_f32_e32 v56, v25
	v_fmac_f32_e32 v39, 0x32a5705f, v24
	v_sub_f32_e32 v25, v25, v56
	v_add_f32_e32 v25, v25, v39
	v_exp_f32_e32 v25, v25
	v_cvt_i32_f32_e32 v39, v56
	v_ldexp_f32 v25, v25, v39
	v_mul_f32_e32 v151, v25, v151
	global_store_dword v[176:177], v151, off
	v_add_u32_e32 v174, 5, v174
	v_lshl_add_u64 v[176:177], v[176:177], 0, s[16:17]
	v_and_b32_e32 v24, 0x1ff, v174
	v_cvt_f32_u32_e32 v24, v24
	v_fmamk_f32 v55, v24, 0xbcc4df2d, v60
	v_mul_f32_e64 v24, |v55|, v173
	v_mul_f32_e32 v25, 0x3fb8aa3b, v24
	v_fma_f32 v39, v24, s4, -v25
	v_rndne_f32_e32 v56, v25
	v_fmac_f32_e32 v39, 0x32a5705f, v24
	v_sub_f32_e32 v25, v25, v56
	v_add_f32_e32 v25, v25, v39
	v_exp_f32_e32 v25, v25
	v_cvt_i32_f32_e32 v39, v56
	v_ldexp_f32 v25, v25, v39
	v_mul_f32_e32 v152, v25, v152
	global_store_dword v[176:177], v152, off
	v_add_u32_e32 v174, 1, v174
	v_lshl_add_u64 v[176:177], v[176:177], 0, s[14:15]
	v_and_b32_e32 v24, 0x1ff, v174
	v_cvt_f32_u32_e32 v24, v24
	v_fmamk_f32 v55, v24, 0xbcc4df2d, v60
	v_mul_f32_e64 v24, |v55|, v173
	v_mul_f32_e32 v25, 0x3fb8aa3b, v24
	v_fma_f32 v39, v24, s4, -v25
	v_rndne_f32_e32 v56, v25
	v_fmac_f32_e32 v39, 0x32a5705f, v24
	v_sub_f32_e32 v25, v25, v56
	v_add_f32_e32 v25, v25, v39
	v_exp_f32_e32 v25, v25
	v_cvt_i32_f32_e32 v39, v56
	v_ldexp_f32 v25, v25, v39
	v_mul_f32_e32 v153, v25, v153
	global_store_dword v[176:177], v153, off
	v_add_u32_e32 v174, 1, v174
	v_lshl_add_u64 v[176:177], v[176:177], 0, s[14:15]
	v_and_b32_e32 v24, 0x1ff, v174
	v_cvt_f32_u32_e32 v24, v24
	v_fmamk_f32 v55, v24, 0xbcc4df2d, v60
	v_mul_f32_e64 v24, |v55|, v173
	v_mul_f32_e32 v25, 0x3fb8aa3b, v24
	v_fma_f32 v39, v24, s4, -v25
	v_rndne_f32_e32 v56, v25
	v_fmac_f32_e32 v39, 0x32a5705f, v24
	v_sub_f32_e32 v25, v25, v56
	v_add_f32_e32 v25, v25, v39
	v_exp_f32_e32 v25, v25
	v_cvt_i32_f32_e32 v39, v56
	v_ldexp_f32 v25, v25, v39
	v_mul_f32_e32 v154, v25, v154
	global_store_dword v[176:177], v154, off
	v_add_u32_e32 v174, 1, v174
	v_lshl_add_u64 v[176:177], v[176:177], 0, s[14:15]
	v_and_b32_e32 v24, 0x1ff, v174
	v_cvt_f32_u32_e32 v24, v24
	v_fmamk_f32 v55, v24, 0xbcc4df2d, v60
	v_mul_f32_e64 v24, |v55|, v173
	v_mul_f32_e32 v25, 0x3fb8aa3b, v24
	v_fma_f32 v39, v24, s4, -v25
	v_rndne_f32_e32 v56, v25
	v_fmac_f32_e32 v39, 0x32a5705f, v24
	v_sub_f32_e32 v25, v25, v56
	v_add_f32_e32 v25, v25, v39
	v_exp_f32_e32 v25, v25
	v_cvt_i32_f32_e32 v39, v56
	v_ldexp_f32 v25, v25, v39
	v_mul_f32_e32 v155, v25, v155
	global_store_dword v[176:177], v155, off
	v_readlane_b32 s12, v254, 39
	v_readlane_b32 s13, v254, 40
	v_readlane_b32 s14, v254, 41
	v_readlane_b32 s15, v254, 42
	v_readlane_b32 s16, v254, 43
	v_readlane_b32 s17, v254, 44
	v_readlane_b32 s18, v254, 45
	v_readlane_b32 s19, v254, 46
	v_readlane_b32 s20, v254, 47
	v_readlane_b32 s21, v254, 48
	v_readlane_b32 s22, v254, 49
	v_readlane_b32 s23, v254, 50
	v_readlane_b32 s24, v254, 51
	v_readlane_b32 s25, v254, 52
	v_readlane_b32 s26, v254, 53
	v_readlane_b32 s27, v254, 54
	v_readlane_b32 s0, v251, 20
	v_readlane_b32 s1, v251, 21
	s_nop 4
	s_load_dword s0, s[0:1], 0x0
	s_waitcnt lgkmcnt(0)
	s_add_i32 s8, s8, s0
	s_cmpk_gt_i32 s8, 0x81f
	s_cbranch_scc0 .LBB0_1321
